# FFN-out epilogue: each second-half residual load issued ahead of the first-half store of the same slot
# baseline (speedup 1.0000x reference)
.LBB0_764:
	s_lshr_b32 s20, s52, 5
	s_mulk_i32 s20, 0x1800
	s_ashr_i32 s21, s20, 31
	s_lshl_b64 s[20:21], s[20:21], 2
	s_add_u32 s20, s74, s20
	v_lshl_add_u32 v166, s52, 8, v148
	s_addc_u32 s21, s75, s21
	v_lshl_or_b32 v168, s53, 8, v150
	s_add_u32 s20, s20, 0xa000
	v_ashrrev_i32_e32 v167, 31, v166
	v_ashrrev_i32_e32 v169, 31, v168
	s_addc_u32 s21, s21, 0
	v_lshlrev_b64 v[146:147], 12, v[166:167]
	v_lshlrev_b64 v[170:171], 2, v[168:169]
	v_lshl_add_u64 v[144:145], s[20:21], 0, v[170:171]
	v_lshl_add_u64 v[146:147], s[72:73], 0, v[146:147]
	v_lshl_add_u64 v[146:147], v[146:147], 0, v[170:171]
	global_load_dwordx4 v[172:175], v[144:145], off
	global_load_dwordx4 v[176:179], v[144:145], off offset:16
	global_load_dwordx4 v[180:183], v[144:145], off offset:512
	global_load_dwordx4 v[184:187], v[144:145], off offset:528
	s_mov_b64 s[20:21], 0x10000
	v_lshl_add_u64 v[154:155], v[146:147], 0, s[20:21]
	s_mov_b64 s[20:21], 0x20000
	v_lshl_add_u64 v[156:157], v[146:147], 0, s[20:21]
	s_mov_b64 s[20:21], 0x30000
	v_lshl_add_u64 v[158:159], v[146:147], 0, s[20:21]
	v_lshl_add_u64 v[160:161], v[146:147], 0, s[12:13]
	v_lshl_add_u64 v[162:163], v[146:147], 0, s[14:15]
	v_lshl_add_u64 v[164:165], v[146:147], 0, s[16:17]
	v_lshl_add_u64 v[166:167], v[146:147], 0, s[4:5]
	global_load_dwordx4 v[190:193], v[146:147], off
	global_load_dwordx4 v[194:197], v[146:147], off offset:16
	global_load_dwordx4 v[198:201], v[146:147], off offset:512
	global_load_dwordx4 v[202:205], v[146:147], off offset:528
	global_load_dwordx4 v[206:209], v[154:155], off
	global_load_dwordx4 v[210:213], v[154:155], off offset:16
	global_load_dwordx4 v[214:217], v[154:155], off offset:512
	global_load_dwordx4 v[218:221], v[154:155], off offset:528
	global_load_dwordx4 v[222:225], v[156:157], off
	global_load_dwordx4 v[226:229], v[156:157], off offset:16
	global_load_dwordx4 v[230:233], v[156:157], off offset:512
	global_load_dwordx4 v[234:237], v[156:157], off offset:528
	global_load_dwordx4 v[238:241], v[158:159], off
	global_load_dwordx4 v[242:245], v[158:159], off offset:16
	global_load_dwordx4 v[246:249], v[158:159], off offset:512
	global_load_dwordx4 v[168:171], v[158:159], off offset:528
	s_waitcnt vmcnt(15)
	v_pk_fma_f32 v[124:125], v[124:125], v[172:173], v[190:191]
	v_pk_fma_f32 v[126:127], v[126:127], v[174:175], v[192:193]
	global_load_dwordx4 v[190:193], v[160:161], off
	global_store_dwordx4 v[146:147], v[124:127], off
	s_waitcnt vmcnt(16)
	v_pk_fma_f32 v[120:121], v[120:121], v[176:177], v[194:195]
	v_pk_fma_f32 v[122:123], v[122:123], v[178:179], v[196:197]
	global_load_dwordx4 v[194:197], v[160:161], off offset:16
	global_store_dwordx4 v[146:147], v[120:123], off offset:16
	s_waitcnt vmcnt(17)
	v_pk_fma_f32 v[116:117], v[116:117], v[180:181], v[198:199]
	v_pk_fma_f32 v[118:119], v[118:119], v[182:183], v[200:201]
	global_load_dwordx4 v[198:201], v[160:161], off offset:512
	global_store_dwordx4 v[146:147], v[116:119], off offset:512
	s_waitcnt vmcnt(18)
	v_pk_fma_f32 v[108:109], v[108:109], v[184:185], v[202:203]
	v_pk_fma_f32 v[110:111], v[110:111], v[186:187], v[204:205]
	global_load_dwordx4 v[202:205], v[160:161], off offset:528
	global_store_dwordx4 v[146:147], v[108:111], off offset:528
	s_waitcnt vmcnt(19)
	v_pk_fma_f32 v[112:113], v[112:113], v[172:173], v[206:207]
	v_pk_fma_f32 v[114:115], v[114:115], v[174:175], v[208:209]
	global_load_dwordx4 v[206:209], v[162:163], off
	global_store_dwordx4 v[154:155], v[112:115], off
	s_waitcnt vmcnt(20)
	v_pk_fma_f32 v[104:105], v[104:105], v[176:177], v[210:211]
	v_pk_fma_f32 v[106:107], v[106:107], v[178:179], v[212:213]
	global_load_dwordx4 v[210:213], v[162:163], off offset:16
	global_store_dwordx4 v[154:155], v[104:107], off offset:16
	s_waitcnt vmcnt(21)
	v_pk_fma_f32 v[100:101], v[100:101], v[180:181], v[214:215]
	v_pk_fma_f32 v[102:103], v[102:103], v[182:183], v[216:217]
	global_load_dwordx4 v[214:217], v[162:163], off offset:512
	global_store_dwordx4 v[154:155], v[100:103], off offset:512
	s_waitcnt vmcnt(22)
	v_pk_fma_f32 v[92:93], v[92:93], v[184:185], v[218:219]
	v_pk_fma_f32 v[94:95], v[94:95], v[186:187], v[220:221]
	global_load_dwordx4 v[218:221], v[162:163], off offset:528
	global_store_dwordx4 v[154:155], v[92:95], off offset:528
	s_waitcnt vmcnt(23)
	v_pk_fma_f32 v[96:97], v[96:97], v[172:173], v[222:223]
	v_pk_fma_f32 v[98:99], v[98:99], v[174:175], v[224:225]
	global_load_dwordx4 v[222:225], v[164:165], off
	global_store_dwordx4 v[156:157], v[96:99], off
	s_waitcnt vmcnt(24)
	v_pk_fma_f32 v[88:89], v[88:89], v[176:177], v[226:227]
	v_pk_fma_f32 v[90:91], v[90:91], v[178:179], v[228:229]
	global_load_dwordx4 v[226:229], v[164:165], off offset:16
	global_store_dwordx4 v[156:157], v[88:91], off offset:16
	s_waitcnt vmcnt(25)
	v_pk_fma_f32 v[84:85], v[84:85], v[180:181], v[230:231]
	v_pk_fma_f32 v[86:87], v[86:87], v[182:183], v[232:233]
	global_load_dwordx4 v[230:233], v[164:165], off offset:512
	global_store_dwordx4 v[156:157], v[84:87], off offset:512
	s_waitcnt vmcnt(26)
	v_pk_fma_f32 v[76:77], v[76:77], v[184:185], v[234:235]
	v_pk_fma_f32 v[78:79], v[78:79], v[186:187], v[236:237]
	global_load_dwordx4 v[234:237], v[164:165], off offset:528
	global_store_dwordx4 v[156:157], v[76:79], off offset:528
	s_waitcnt vmcnt(27)
	v_pk_fma_f32 v[80:81], v[80:81], v[172:173], v[238:239]
	v_pk_fma_f32 v[82:83], v[82:83], v[174:175], v[240:241]
	global_load_dwordx4 v[238:241], v[166:167], off
	global_store_dwordx4 v[158:159], v[80:83], off
	s_waitcnt vmcnt(28)
	v_pk_fma_f32 v[72:73], v[72:73], v[176:177], v[242:243]
	v_pk_fma_f32 v[74:75], v[74:75], v[178:179], v[244:245]
	global_load_dwordx4 v[242:245], v[166:167], off offset:16
	global_store_dwordx4 v[158:159], v[72:75], off offset:16
	s_waitcnt vmcnt(29)
	v_pk_fma_f32 v[68:69], v[68:69], v[180:181], v[246:247]
	v_pk_fma_f32 v[70:71], v[70:71], v[182:183], v[248:249]
	global_load_dwordx4 v[246:249], v[166:167], off offset:512
	global_store_dwordx4 v[158:159], v[68:71], off offset:512
	s_waitcnt vmcnt(30)
	v_pk_fma_f32 v[64:65], v[64:65], v[184:185], v[168:169]
	v_pk_fma_f32 v[66:67], v[66:67], v[186:187], v[170:171]
	global_load_dwordx4 v[168:171], v[166:167], off offset:528
	global_store_dwordx4 v[158:159], v[64:67], off offset:528
	s_waitcnt vmcnt(31)
	v_pk_fma_f32 v[60:61], v[60:61], v[172:173], v[190:191]
	v_pk_fma_f32 v[62:63], v[62:63], v[174:175], v[192:193]
	global_store_dwordx4 v[160:161], v[60:63], off
	s_waitcnt vmcnt(30)
	v_pk_fma_f32 v[56:57], v[56:57], v[176:177], v[194:195]
	v_pk_fma_f32 v[58:59], v[58:59], v[178:179], v[196:197]
	global_store_dwordx4 v[160:161], v[56:59], off offset:16
	s_waitcnt vmcnt(29)
	v_pk_fma_f32 v[52:53], v[52:53], v[180:181], v[198:199]
	v_pk_fma_f32 v[54:55], v[54:55], v[182:183], v[200:201]
	global_store_dwordx4 v[160:161], v[52:55], off offset:512
	s_waitcnt vmcnt(28)
	v_pk_fma_f32 v[48:49], v[48:49], v[184:185], v[202:203]
	v_pk_fma_f32 v[50:51], v[50:51], v[186:187], v[204:205]
	global_store_dwordx4 v[160:161], v[48:51], off offset:528
	s_waitcnt vmcnt(27)
	v_pk_fma_f32 v[44:45], v[44:45], v[172:173], v[206:207]
	v_pk_fma_f32 v[46:47], v[46:47], v[174:175], v[208:209]
	global_store_dwordx4 v[162:163], v[44:47], off
	s_waitcnt vmcnt(26)
	v_pk_fma_f32 v[40:41], v[40:41], v[176:177], v[210:211]
	v_pk_fma_f32 v[42:43], v[42:43], v[178:179], v[212:213]
	global_store_dwordx4 v[162:163], v[40:43], off offset:16
	s_waitcnt vmcnt(25)
	v_pk_fma_f32 v[36:37], v[36:37], v[180:181], v[214:215]
	v_pk_fma_f32 v[38:39], v[38:39], v[182:183], v[216:217]
	global_store_dwordx4 v[162:163], v[36:39], off offset:512
	s_waitcnt vmcnt(24)
	v_pk_fma_f32 v[32:33], v[32:33], v[184:185], v[218:219]
	v_pk_fma_f32 v[34:35], v[34:35], v[186:187], v[220:221]
	global_store_dwordx4 v[162:163], v[32:35], off offset:528
	s_waitcnt vmcnt(23)
	v_pk_fma_f32 v[28:29], v[28:29], v[172:173], v[222:223]
	v_pk_fma_f32 v[30:31], v[30:31], v[174:175], v[224:225]
	global_store_dwordx4 v[164:165], v[28:31], off
	s_waitcnt vmcnt(22)
	v_pk_fma_f32 v[24:25], v[24:25], v[176:177], v[226:227]
	v_pk_fma_f32 v[26:27], v[26:27], v[178:179], v[228:229]
	global_store_dwordx4 v[164:165], v[24:27], off offset:16
	s_waitcnt vmcnt(21)
	v_pk_fma_f32 v[20:21], v[20:21], v[180:181], v[230:231]
	v_pk_fma_f32 v[22:23], v[22:23], v[182:183], v[232:233]
	global_store_dwordx4 v[164:165], v[20:23], off offset:512
	s_waitcnt vmcnt(20)
	v_pk_fma_f32 v[16:17], v[16:17], v[184:185], v[234:235]
	v_pk_fma_f32 v[18:19], v[18:19], v[186:187], v[236:237]
	global_store_dwordx4 v[164:165], v[16:19], off offset:528
	s_waitcnt vmcnt(19)
	v_pk_fma_f32 v[12:13], v[12:13], v[172:173], v[238:239]
	v_pk_fma_f32 v[14:15], v[14:15], v[174:175], v[240:241]
	global_store_dwordx4 v[166:167], v[12:15], off
	s_waitcnt vmcnt(18)
	v_pk_fma_f32 v[8:9], v[8:9], v[176:177], v[242:243]
	v_pk_fma_f32 v[10:11], v[10:11], v[178:179], v[244:245]
	global_store_dwordx4 v[166:167], v[8:11], off offset:16
	s_waitcnt vmcnt(17)
	v_pk_fma_f32 v[4:5], v[4:5], v[180:181], v[246:247]
	v_pk_fma_f32 v[6:7], v[6:7], v[182:183], v[248:249]
	global_store_dwordx4 v[166:167], v[4:7], off offset:512
	s_waitcnt vmcnt(16)
	v_pk_fma_f32 v[0:1], v[0:1], v[184:185], v[168:169]
	v_pk_fma_f32 v[2:3], v[2:3], v[186:187], v[170:171]
	global_store_dwordx4 v[166:167], v[0:3], off offset:528
	s_and_b64 vcc, exec, s[0:1]
	s_mov_b64 s[0:1], -1
	s_cbranch_vccnz .LBB0_749
	s_andn2_b64 vcc, exec, s[6:7]
	s_cbranch_vccnz .LBB0_748
	s_barrier
	s_branch .LBB0_748
